# S5 end-state pass: table loads of a direction issued together before one wait
# baseline (speedup 1.0000x reference)
.LBB0_321:
	v_lshl_or_b32 v112, s15, 5, v75
	v_lshlrev_b64 v[0:1], 10, v[112:113]
	v_lshl_add_u64 v[0:1], v[58:59], 0, v[0:1]
	v_lshlrev_b64 v[2:3], 12, v[112:113]
	v_lshl_add_u64 v[2:3], v[60:61], 0, v[2:3]
	global_load_dwordx2 v[24:25], v[0:1], off
	global_load_dwordx4 v[26:29], v[2:3], off
	global_load_dwordx4 v[30:33], v[2:3], off offset:1024
	global_load_dwordx4 v[34:37], v[2:3], off offset:2048
	global_load_dwordx4 v[38:41], v[2:3], off offset:3072
	s_waitcnt vmcnt(0) lgkmcnt(0)
	s_and_b64 s[8:9], s[6:7], exec
	v_mov_b32_e32 v66, 0
	s_mov_b64 s[10:11], -1
	s_mov_b64 s[12:13], s[6:7]
	s_cselect_b32 s16, 0, 32
	s_cselect_b32 s17, 32, 0
	s_xor_b64 s[8:9], s[6:7], -1
	v_mov_b32_e32 v67, v66
	v_pk_mov_b32 v[64:65], v[24:25], v[24:25] op_sel:[1,0]
	s_branch .LBB0_324
